# post-norm phase after FFN1: the gain-load/store ladder de-serialised (four gain loads issued once into spare registers, one wait instead of eight store-ack waits)
# speedup vs baseline: 1.0005x; 1.0005x over previous
; DEVI float bflo(unsigned v) { return __uint_as_float(v << 16); }
; DEVI float bfhi(unsigned v) { return __uint_as_float(v & 0xffff0000u); }
; DEVI size_t blk_off(int row, int col) { return ((size_t)(col >> 5) * MROWS + row) * 32 + (col & 31); }
; DEVI void postnorm_phase(const Params& p, const bf16_t* y, int ldy, float coef, const float* g_post, const float* g_pre,
;                          int src_mode, bool write_h, bf16_t* a_out, bool yblk) {
;     ...
;     f32x4 h[2][4];
;     u32x2 yw[2][4];
; #pragma unroll
;     for (int u = 0; u < 2; ++u) {
;       const float* hs = h_src(p, src_mode, s, t + u, Lr);
; #pragma unroll
;       for (int i = 0; i < 4; ++i) h[u][i] = __builtin_nontemporal_load((const f32x4*)(hs + i * 256 + lane * 4));
;       if (y) {
; #pragma unroll
;         for (int i = 0; i < 4; ++i)
;           yw[u][i] = *(const u32x2*)(y + (yblk ? blk_off(row0 + u, i * 256 + lane * 4) : (size_t)(row0 + u) * ldy + i * 256 + lane * 4));
;       }
;     }
; #pragma unroll
;     for (int u = 0; u < 2; ++u) {
;       if (y) {
;         f32x4 yv[4]; float ss = 0.f;
; #pragma unroll
;         for (int i = 0; i < 4; ++i) {
;           const u32x2 w = yw[u][i];
;           yv[i] = (f32x4){bflo(w.x), bfhi(w.x), bflo(w.y), bfhi(w.y)};
;           ss += yv[i][0] * yv[i][0] + yv[i][1] * yv[i][1] + yv[i][2] * yv[i][2] + yv[i][3] * yv[i][3];
;         }
;         ss = wave_sum(ss);
;         const float rstd = rsqrtf(ss * (1.0f / DM) + EPSF) * coef;
.LBB0_434:
	s_or_b64 exec, exec, s[8:9]
	v_lshl_add_u64 v[32:33], v[18:19], 0, v[46:47]
	v_lshlrev_b64 v[32:33], 6, v[32:33]
	v_lshl_add_u64 v[70:71], v[40:41], 0, v[32:33]
	v_lshl_add_u64 v[32:33], v[18:19], 0, v[48:49]
	v_lshlrev_b64 v[32:33], 6, v[32:33]
	v_lshl_add_u64 v[68:69], v[40:41], 0, v[32:33]
	v_lshl_add_u64 v[32:33], v[18:19], 0, v[50:51]
	v_lshl_add_u64 v[18:19], v[18:19], 0, v[52:53]
	v_lshlrev_b64 v[64:65], 6, v[18:19]
	global_load_dwordx2 v[88:89], v[68:69], off
	global_load_dwordx2 v[96:97], v[70:71], off
	v_lshlrev_b64 v[32:33], 6, v[32:33]
	v_lshl_add_u64 v[18:19], v[40:41], 0, v[64:65]
	v_lshl_add_u64 v[66:67], v[40:41], 0, v[32:33]
	global_load_dwordx2 v[122:123], v[18:19], off
	global_load_dwordx2 v[124:125], v[66:67], off
	v_sub_u32_e32 v109, v35, v34
	global_load_dwordx4 v[110:113], v[42:43], off
	global_load_dwordx4 v[114:117], v[42:43], off offset:1024
	global_load_dwordx4 v[118:121], v[42:43], off offset:2048
	global_load_dwordx4 v[34:37], v[42:43], off offset:3072
	s_waitcnt vmcnt(10)
	v_and_b32_e32 v93, 0xffff0000, v28
	v_and_b32_e32 v92, 0xffff0000, v24
	v_lshlrev_b32_e32 v87, 16, v28
	v_lshlrev_b32_e32 v86, 16, v24
	s_waitcnt vmcnt(9)
	v_lshlrev_b32_e32 v76, 16, v20
	s_waitcnt vmcnt(8)
	v_and_b32_e32 v79, 0xffff0000, v22
	v_and_b32_e32 v78, 0xffff0000, v20
	v_lshlrev_b32_e32 v82, 16, v21
	v_and_b32_e32 v84, 0xffff0000, v21
	v_and_b32_e32 v24, 64, v203
	v_pk_mul_f32 v[20:21], v[92:93], v[92:93]
	v_lshlrev_b32_e32 v95, 16, v29
	v_lshlrev_b32_e32 v94, 16, v25
	v_and_b32_e32 v98, 0xffff0000, v25
	v_lshlrev_b32_e32 v77, 16, v22
	v_lshlrev_b32_e32 v83, 16, v23
	v_and_b32_e32 v85, 0xffff0000, v23
	v_xor_b32_e32 v25, 32, v203
	v_pk_mul_f32 v[22:23], v[78:79], v[78:79]
	v_add_u32_e32 v75, 64, v24
	v_pk_fma_f32 v[80:81], v[86:87], v[86:87], v[20:21]
	v_and_b32_e32 v99, 0xffff0000, v29
	v_pk_fma_f32 v[90:91], v[76:77], v[76:77], v[22:23]
	v_cmp_lt_i32_e32 vcc, v25, v75
	v_pk_fma_f32 v[80:81], v[94:95], v[94:95], v[80:81]
	v_pk_fma_f32 v[90:91], v[82:83], v[82:83], v[90:91]
	v_cndmask_b32_e32 v100, v203, v25, vcc
	v_pk_fma_f32 v[126:127], v[98:99], v[98:99], v[80:81]
	v_lshlrev_b32_e32 v183, 2, v100
	v_pk_fma_f32 v[128:129], v[84:85], v[84:85], v[90:91]
	v_mov_b32_e32 v181, v126
	v_xor_b32_e32 v28, 16, v203
	v_cmp_lt_i32_e32 vcc, v28, v75
	v_readlane_b32 s44, v250, 1
	v_readlane_b32 s45, v250, 2
	v_cndmask_b32_e32 v182, v203, v28, vcc
	v_lshlrev_b32_e32 v182, 2, v182
	s_mov_b64 s[8:9], s[44:45]
	v_lshlrev_b64 v[18:19], 12, v[30:31]
	v_lshl_add_u64 v[18:19], v[26:27], 0, v[18:19]
	v_lshl_add_u64 v[18:19], v[18:19], 0, v[0:1]
	global_load_dwordx4 v[30:33], v[18:19], off nt
	global_load_dwordx4 v[26:29], v[18:19], off offset:1024 nt
	global_load_dwordx4 v[22:25], v[18:19], off offset:2048 nt
	s_nop 0
	global_load_dwordx4 v[18:21], v[18:19], off offset:3072 nt
	v_readlane_b32 s46, v250, 3
	v_readlane_b32 s47, v250, 4
	s_waitcnt vmcnt(11)
	v_and_b32_e32 v81, 0xffff0000, v88
	s_waitcnt vmcnt(10)
	v_and_b32_e32 v80, 0xffff0000, v96
	v_lshlrev_b32_e32 v105, 16, v88
	v_lshlrev_b32_e32 v104, 16, v96
	v_lshlrev_b32_e32 v101, 16, v89
	v_lshlrev_b32_e32 v100, 16, v97
	v_and_b32_e32 v91, 0xffff0000, v89
	v_and_b32_e32 v90, 0xffff0000, v97
	s_waitcnt vmcnt(9)
	v_lshlrev_b32_e32 v103, 16, v122
	v_and_b32_e32 v89, 0xffff0000, v122
	s_waitcnt vmcnt(8)
	v_and_b32_e32 v88, 0xffff0000, v124
	v_lshlrev_b32_e32 v107, 16, v123
	v_and_b32_e32 v97, 0xffff0000, v123
	v_pk_mul_f32 v[122:123], v[80:81], v[80:81]
	v_lshlrev_b32_e32 v102, 16, v124
	v_lshlrev_b32_e32 v106, 16, v125
	v_and_b32_e32 v96, 0xffff0000, v125
	v_pk_mul_f32 v[124:125], v[88:89], v[88:89]
	v_pk_fma_f32 v[122:123], v[104:105], v[104:105], v[122:123]
	v_pk_fma_f32 v[124:125], v[102:103], v[102:103], v[124:125]
	v_pk_fma_f32 v[122:123], v[100:101], v[100:101], v[122:123]
	v_pk_fma_f32 v[124:125], v[106:107], v[106:107], v[124:125]
	v_pk_fma_f32 v[122:123], v[90:91], v[90:91], v[122:123]
	v_pk_fma_f32 v[124:125], v[96:97], v[96:97], v[124:125]
	v_mov_b32_e32 v180, v122
	v_mov_b32_e32 v126, v123
	v_mov_b32_e32 v122, v124
	v_pk_add_f32 v[126:127], v[180:181], v[126:127]
	v_mov_b32_e32 v123, v128
	v_pk_add_f32 v[122:123], v[126:127], v[122:123]
	v_mov_b32_e32 v128, v125
	v_pk_add_f32 v[122:123], v[122:123], v[128:129]
	ds_bpermute_b32 v125, v183, v123
	ds_bpermute_b32 v124, v183, v122
	v_xor_b32_e32 v126, 8, v203
	v_cmp_lt_i32_e32 vcc, v126, v75
	v_mov_b32_e32 v127, s9
	v_mov_b32_e32 v129, v92
	s_waitcnt lgkmcnt(0)
	v_pk_add_f32 v[122:123], v[122:123], v[124:125]
	ds_bpermute_b32 v125, v182, v123
	ds_bpermute_b32 v124, v182, v122
	v_cndmask_b32_e32 v126, v203, v126, vcc
	v_lshlrev_b32_e32 v184, 2, v126
	v_xor_b32_e32 v126, 4, v203
	v_cmp_lt_i32_e32 vcc, v126, v75
	s_waitcnt lgkmcnt(0)
	v_pk_add_f32 v[122:123], v[122:123], v[124:125]
	ds_bpermute_b32 v125, v184, v123
	ds_bpermute_b32 v124, v184, v122
	v_cndmask_b32_e32 v126, v203, v126, vcc
	v_lshlrev_b32_e32 v185, 2, v126
	v_xor_b32_e32 v126, 2, v203
	v_cmp_lt_i32_e32 vcc, v126, v75
	s_waitcnt lgkmcnt(0)
	v_pk_add_f32 v[122:123], v[122:123], v[124:125]
	ds_bpermute_b32 v125, v185, v123
	ds_bpermute_b32 v124, v185, v122
	v_cndmask_b32_e32 v126, v203, v126, vcc
	v_lshlrev_b32_e32 v186, 2, v126
	v_xor_b32_e32 v126, 1, v203
	v_cmp_lt_i32_e32 vcc, v126, v75
	s_waitcnt lgkmcnt(0)
	v_pk_add_f32 v[122:123], v[122:123], v[124:125]
	ds_bpermute_b32 v125, v186, v123
	ds_bpermute_b32 v124, v186, v122
	v_cndmask_b32_e32 v75, v203, v126, vcc
	v_lshlrev_b32_e32 v187, 2, v75
	v_cndmask_b32_e64 v75, v109, v108, s[0:1]
	v_add_u32_e32 v126, v75, v74
	s_waitcnt lgkmcnt(0)
; DEVI void postnorm_phase(const Params& p, const bf16_t* y, int ldy, float coef, const float* g_post, const float* g_pre,
;                          int src_mode, bool write_h, bf16_t* a_out, bool yblk) {
;     ...
;         const float rstd = rsqrtf(ss * (1.0f / DM) + EPSF) * coef;
; #pragma unroll
;         for (int i = 0; i < 4; ++i) {
;           const f32x4 g = *(const f32x4*)(g_post + i * 256 + lane * 4);
;           h[u][i] += yv[i] * rstd * g;
;         }
;       }
;       if (write_h) {
;         float* hd = h_dst(p, s, t + u, Lr);
; #pragma unroll
;         for (int i = 0; i < 4; ++i) __builtin_nontemporal_store(h[u][i], (f32x4*)(hd + i * 256 + lane * 4));
	v_pk_add_f32 v[74:75], v[122:123], v[124:125]
	ds_bpermute_b32 v123, v187, v75
	ds_bpermute_b32 v122, v187, v74
	v_mov_b32_e32 v124, s8
	v_cndmask_b32_e64 v125, v155, v127, s[0:1]
	v_cndmask_b32_e64 v124, v154, v124, s[0:1]
	s_mov_b32 s0, 0x358637bd
	s_waitcnt lgkmcnt(0)
	v_pk_add_f32 v[122:123], v[74:75], v[122:123]
	v_mov_b64_e32 v[74:75], s[0:1]
	s_mov_b32 s0, 0x3a800000
	v_pk_fma_f32 v[122:123], v[122:123], s[0:1], v[74:75] op_sel_hi:[1,0,0]
	s_mov_b32 s1, 0x800000
	v_mul_f32_e32 v128, 0x4b800000, v123
	v_cmp_gt_f32_e32 vcc, s1, v123
	v_ashrrev_i32_e32 v127, 31, v126
	v_lshlrev_b64 v[126:127], 12, v[126:127]
	v_cndmask_b32_e32 v123, v123, v128, vcc
	v_rsq_f32_e32 v123, v123
	v_lshl_add_u64 v[124:125], v[124:125], 0, v[126:127]
	v_mov_b32_e32 v181, v98
	v_mov_b32_e32 v92, v87
	v_mul_f32_e32 v126, 0x45800000, v123
	v_cndmask_b32_e32 v123, v123, v126, vcc
	v_mul_f32_e32 v126, 0.5, v123
	v_mov_b32_e32 v98, v95
	v_mov_b32_e32 v128, v86
	v_mov_b32_e32 v180, v94
	v_pk_mul_f32 v[86:87], v[92:93], v[126:127] op_sel_hi:[1,0]
	v_pk_mul_f32 v[92:93], v[98:99], v[126:127] op_sel_hi:[1,0]
	v_pk_mul_f32 v[128:129], v[128:129], v[126:127] op_sel_hi:[1,0]
	v_pk_mul_f32 v[180:181], v[180:181], v[126:127] op_sel_hi:[1,0]
	s_waitcnt vmcnt(6)
	v_pk_fma_f32 v[12:13], v[116:117], v[92:93], v[12:13]
	v_pk_fma_f32 v[10:11], v[114:115], v[86:87], v[10:11]
	v_mov_b32_e32 v86, v76
	v_mov_b32_e32 v87, v78
	v_mov_b32_e32 v92, v82
	v_mov_b32_e32 v93, v84
	v_mov_b32_e32 v78, v77
	v_mov_b32_e32 v84, v83
	v_lshl_add_u64 v[124:125], v[124:125], 0, v[0:1]
	v_pk_fma_f32 v[16:17], v[112:113], v[180:181], v[16:17]
	v_pk_fma_f32 v[14:15], v[110:111], v[128:129], v[14:15]
	v_pk_mul_f32 v[86:87], v[86:87], v[126:127] op_sel_hi:[1,0]
	v_pk_mul_f32 v[92:93], v[92:93], v[126:127] op_sel_hi:[1,0]
	v_pk_mul_f32 v[76:77], v[78:79], v[126:127] op_sel_hi:[1,0]
	v_pk_mul_f32 v[78:79], v[84:85], v[126:127] op_sel_hi:[1,0]
	s_waitcnt vmcnt(5)
	v_pk_fma_f32 v[8:9], v[120:121], v[92:93], v[8:9]
	v_pk_fma_f32 v[6:7], v[118:119], v[86:87], v[6:7]
	s_waitcnt vmcnt(4)
	v_pk_fma_f32 v[4:5], v[36:37], v[78:79], v[4:5]
	v_pk_fma_f32 v[2:3], v[34:35], v[76:77], v[2:3]
	global_store_dwordx4 v[124:125], v[14:17], off nt
	global_store_dwordx4 v[124:125], v[10:13], off offset:1024 nt
	global_store_dwordx4 v[124:125], v[6:9], off offset:2048 nt
	global_store_dwordx4 v[124:125], v[2:5], off offset:3072 nt
	global_load_dwordx4 v[34:37], v[42:43], off
	global_load_dwordx4 v[76:79], v[42:43], off offset:1024
	global_load_dwordx4 v[82:85], v[42:43], off offset:2048
	global_load_dwordx4 v[92:95], v[42:43], off offset:3072
	v_cndmask_b32_e64 v86, v109, v108, s[52:53]
	v_add_u32_e32 v86, v86, v55
	v_mul_f32_e32 v55, 0x4b800000, v122
	v_cmp_gt_f32_e32 vcc, s1, v122
	v_mov_b32_e32 v98, v100
	v_mov_b32_e32 v108, v104
	v_cndmask_b32_e32 v55, v122, v55, vcc
	v_rsq_f32_e32 v55, v55
	v_mov_b32_e32 v109, v80
	v_ashrrev_i32_e32 v87, 31, v86
	v_mov_b32_e32 v110, v102
	v_mul_f32_e32 v100, 0x45800000, v55
	v_cndmask_b32_e32 v55, v55, v100, vcc
	v_mul_f32_e32 v100, 0.5, v55
	v_mov_b32_e32 v111, v88
	v_mov_b32_e32 v88, v103
	v_pk_mul_f32 v[102:103], v[108:109], v[100:101] op_sel_hi:[1,0]
	v_mov_b32_e32 v99, v90
	v_mov_b32_e32 v80, v105
	v_mov_b32_e32 v104, v106
	v_mov_b32_e32 v105, v96
	v_mov_b32_e32 v90, v101
	v_mov_b32_e32 v96, v107
	v_pk_mul_f32 v[98:99], v[98:99], v[100:101] op_sel_hi:[1,0]
	v_pk_mul_f32 v[90:91], v[90:91], v[100:101] op_sel_hi:[1,0]
	v_pk_mul_f32 v[80:81], v[80:81], v[100:101] op_sel_hi:[1,0]
	v_pk_mul_f32 v[104:105], v[104:105], v[100:101] op_sel_hi:[1,0]
	v_pk_mul_f32 v[106:107], v[110:111], v[100:101] op_sel_hi:[1,0]
	v_pk_mul_f32 v[96:97], v[96:97], v[100:101] op_sel_hi:[1,0]
	v_pk_mul_f32 v[88:89], v[88:89], v[100:101] op_sel_hi:[1,0]
	s_waitcnt vmcnt(3)
	v_pk_fma_f32 v[30:31], v[34:35], v[102:103], v[30:31]
	v_lshlrev_b64 v[34:35], 12, v[86:87]
	v_lshl_add_u64 v[34:35], v[72:73], 0, v[34:35]
	v_pk_fma_f32 v[32:33], v[36:37], v[98:99], v[32:33]
	v_lshl_add_u64 v[34:35], v[34:35], 0, v[0:1]
	v_mov_b32_e32 v36, v15
	v_mov_b32_e32 v37, v11
	s_waitcnt vmcnt(2)
	v_pk_fma_f32 v[26:27], v[76:77], v[80:81], v[26:27]
	v_pk_fma_f32 v[28:29], v[78:79], v[90:91], v[28:29]
	s_waitcnt vmcnt(1)
	v_pk_fma_f32 v[22:23], v[82:83], v[106:107], v[22:23]
	v_pk_fma_f32 v[24:25], v[84:85], v[104:105], v[24:25]
	s_waitcnt vmcnt(0)
; DEVI unsigned pk2(float lo, float hi) { const f32x2_t v = {lo, hi}; const bf16x2_t b = __builtin_convertvector(v, bf16x2_t); return __builtin_bit_cast(unsigned, b); }
; DEVI size_t blk_off(int row, int col) { return ((size_t)(col >> 5) * MROWS + row) * 32 + (col & 31); }
; DEVI void postnorm_phase(const Params& p, const bf16_t* y, int ldy, float coef, const float* g_post, const float* g_pre,
;                          int src_mode, bool write_h, bf16_t* a_out, bool yblk) {
;     ...
;     if (a_out) {
; #pragma unroll
;       for (int u = 0; u < 2; ++u) {
;         float ss = 0.f;
; #pragma unroll
;         for (int i = 0; i < 4; ++i) ss += h[u][i][0] * h[u][i][0] + h[u][i][1] * h[u][i][1] + h[u][i][2] * h[u][i][2] + h[u][i][3] * h[u][i][3];
;         ss = wave_sum(ss);
;         const float rstd = rsqrtf(ss * (1.0f / DM) + EPSF);
; #pragma unroll
;         for (int i = 0; i < 4; ++i) {
;           const f32x4 g = *(const f32x4*)(g_pre + i * 256 + lane * 4);
;           const f32x4 v = h[u][i] * rstd * g;
;           *(u32x2*)(a_out + blk_off(row0 + u, i * 256 + lane * 4)) = (u32x2){pk2(v[0], v[1]), pk2(v[2], v[3])};
;         }
;       }
	v_pk_fma_f32 v[18:19], v[92:93], v[88:89], v[18:19]
	v_pk_fma_f32 v[20:21], v[94:95], v[96:97], v[20:21]
	global_store_dwordx4 v[34:35], v[30:33], off nt
	global_store_dwordx4 v[34:35], v[26:29], off offset:1024 nt
	global_store_dwordx4 v[34:35], v[22:25], off offset:2048 nt
	global_store_dwordx4 v[34:35], v[18:21], off offset:3072 nt
	v_mov_b32_e32 v34, v14
	v_mov_b32_e32 v35, v10
	v_pk_mul_f32 v[36:37], v[36:37], v[36:37]
	v_mov_b32_e32 v80, v31
	v_pk_fma_f32 v[34:35], v[34:35], v[34:35], v[36:37]
	v_mov_b32_e32 v36, v16
	v_mov_b32_e32 v37, v12
	v_pk_fma_f32 v[34:35], v[36:37], v[36:37], v[34:35]
	v_mov_b32_e32 v36, v17
	v_mov_b32_e32 v37, v13
	v_pk_fma_f32 v[72:73], v[36:37], v[36:37], v[34:35]
	v_mov_b32_e32 v36, v3
	v_mov_b32_e32 v37, v7
	v_mov_b32_e32 v34, v2
	v_mov_b32_e32 v35, v6
	v_pk_mul_f32 v[36:37], v[36:37], v[36:37]
	v_mov_b32_e32 v81, v27
	v_pk_fma_f32 v[34:35], v[34:35], v[34:35], v[36:37]
	v_mov_b32_e32 v36, v4
	v_mov_b32_e32 v37, v8
	v_pk_fma_f32 v[34:35], v[36:37], v[36:37], v[34:35]
	v_mov_b32_e32 v36, v5
	v_mov_b32_e32 v37, v9
	v_pk_fma_f32 v[76:77], v[36:37], v[36:37], v[34:35]
	global_load_dwordx4 v[230:233], v[44:45], off
	global_load_dwordx4 v[234:237], v[44:45], off offset:1024
	global_load_dwordx4 v[238:241], v[44:45], off offset:2048
	global_load_dwordx4 v[242:245], v[44:45], off offset:3072
	v_mov_b32_e32 v78, v30
	v_mov_b32_e32 v79, v26
	v_pk_mul_f32 v[80:81], v[80:81], v[80:81]
	v_mov_b32_e32 v82, v19
	v_pk_fma_f32 v[78:79], v[78:79], v[78:79], v[80:81]
	v_mov_b32_e32 v80, v32
	v_mov_b32_e32 v81, v28
	v_pk_fma_f32 v[78:79], v[80:81], v[80:81], v[78:79]
	v_mov_b32_e32 v80, v33
	v_mov_b32_e32 v81, v29
	v_mov_b32_e32 v83, v23
	v_pk_fma_f32 v[78:79], v[80:81], v[80:81], v[78:79]
	v_mov_b32_e32 v80, v18
	v_mov_b32_e32 v81, v22
	v_pk_mul_f32 v[82:83], v[82:83], v[82:83]
	s_nop 0
	v_pk_fma_f32 v[80:81], v[80:81], v[80:81], v[82:83]
	v_mov_b32_e32 v82, v20
	v_mov_b32_e32 v83, v24
	v_pk_fma_f32 v[80:81], v[82:83], v[82:83], v[80:81]
	v_mov_b32_e32 v82, v21
	v_mov_b32_e32 v83, v25
	v_pk_fma_f32 v[80:81], v[82:83], v[82:83], v[80:81]
	v_mov_b32_e32 v82, v78
	v_mov_b32_e32 v83, v72
	v_mov_b32_e32 v72, v79
	v_pk_add_f32 v[72:73], v[82:83], v[72:73]
	v_mov_b32_e32 v78, v81
	v_mov_b32_e32 v79, v77
	v_pk_add_f32 v[72:73], v[78:79], v[72:73]
	v_mov_b32_e32 v81, v76
	v_pk_add_f32 v[72:73], v[80:81], v[72:73]
	ds_bpermute_b32 v77, v183, v73
	ds_bpermute_b32 v76, v183, v72
	s_waitcnt lgkmcnt(0)
	v_pk_add_f32 v[72:73], v[72:73], v[76:77]
	ds_bpermute_b32 v77, v182, v73
	ds_bpermute_b32 v76, v182, v72
	s_waitcnt lgkmcnt(0)
	v_pk_add_f32 v[72:73], v[72:73], v[76:77]
	ds_bpermute_b32 v77, v184, v73
	ds_bpermute_b32 v76, v184, v72
	s_waitcnt lgkmcnt(0)
	v_pk_add_f32 v[72:73], v[72:73], v[76:77]
	ds_bpermute_b32 v77, v185, v73
	ds_bpermute_b32 v76, v185, v72
	s_waitcnt lgkmcnt(0)
	v_pk_add_f32 v[72:73], v[72:73], v[76:77]
	ds_bpermute_b32 v77, v186, v73
	ds_bpermute_b32 v76, v186, v72
	s_waitcnt lgkmcnt(0)
	v_pk_add_f32 v[72:73], v[72:73], v[76:77]
	ds_bpermute_b32 v77, v187, v73
	ds_bpermute_b32 v76, v187, v72
	s_waitcnt lgkmcnt(0)
	v_pk_add_f32 v[72:73], v[72:73], v[76:77]
	s_nop 0
	v_pk_fma_f32 v[72:73], v[72:73], s[0:1], v[74:75] op_sel_hi:[1,0,0]
	s_nop 0
	v_mul_f32_e32 v0, 0x4b800000, v73
	v_cmp_gt_f32_e32 vcc, s1, v73
	s_nop 1
	v_cndmask_b32_e32 v0, v73, v0, vcc
	v_rsq_f32_e32 v0, v0
	s_nop 0
	v_mul_f32_e32 v55, 0x45800000, v0
	v_cndmask_b32_e32 v0, v0, v55, vcc
	v_pk_mul_f32 v[14:15], v[14:15], v[0:1] op_sel_hi:[1,0]
	v_pk_mul_f32 v[16:17], v[16:17], v[0:1] op_sel_hi:[1,0]
	s_waitcnt vmcnt(0)
	v_pk_mul_f32 v[14:15], v[230:231], v[14:15]
	v_pk_mul_f32 v[16:17], v[232:233], v[16:17]
	v_cvt_pk_bf16_f32 v14, v14, v15
	v_cvt_pk_bf16_f32 v15, v16, v17
	global_store_dwordx2 v[62:63], v[14:15], off
	v_pk_mul_f32 v[10:11], v[10:11], v[0:1] op_sel_hi:[1,0]
	v_pk_mul_f32 v[12:13], v[12:13], v[0:1] op_sel_hi:[1,0]
	v_pk_mul_f32 v[6:7], v[6:7], v[0:1] op_sel_hi:[1,0]
	v_pk_mul_f32 v[8:9], v[8:9], v[0:1] op_sel_hi:[1,0]
	v_pk_mul_f32 v[2:3], v[2:3], v[0:1] op_sel_hi:[1,0]
	v_pk_mul_f32 v[4:5], v[4:5], v[0:1] op_sel_hi:[1,0]
	v_mul_f32_e32 v0, 0x4b800000, v72
	v_cmp_gt_f32_e32 vcc, s1, v72
	v_pk_mul_f32 v[12:13], v[236:237], v[12:13]
	v_pk_mul_f32 v[10:11], v[234:235], v[10:11]
	v_cndmask_b32_e32 v0, v72, v0, vcc
	v_cvt_pk_bf16_f32 v10, v10, v11
	v_cvt_pk_bf16_f32 v11, v12, v13
	global_store_dwordx2 v[60:61], v[10:11], off
	v_rsq_f32_e32 v0, v0
	v_pk_mul_f32 v[8:9], v[240:241], v[8:9]
	v_pk_mul_f32 v[6:7], v[238:239], v[6:7]
	s_nop 0
	v_cvt_pk_bf16_f32 v6, v6, v7
	v_cvt_pk_bf16_f32 v7, v8, v9
	global_store_dwordx2 v[58:59], v[6:7], off
	v_pk_mul_f32 v[4:5], v[244:245], v[4:5]
	v_pk_mul_f32 v[2:3], v[242:243], v[2:3]
	v_mul_f32_e32 v6, 0x45800000, v0
	v_cvt_pk_bf16_f32 v2, v2, v3
	v_cvt_pk_bf16_f32 v3, v4, v5
	global_store_dwordx2 v[56:57], v[2:3], off
	v_cndmask_b32_e32 v0, v0, v6, vcc
	v_pk_mul_f32 v[6:7], v[30:31], v[0:1] op_sel_hi:[1,0]
	v_pk_mul_f32 v[8:9], v[32:33], v[0:1] op_sel_hi:[1,0]
	v_pk_mul_f32 v[2:3], v[230:231], v[6:7]
	v_pk_mul_f32 v[4:5], v[232:233], v[8:9]
	v_cvt_pk_bf16_f32 v2, v2, v3
	v_cvt_pk_bf16_f32 v3, v4, v5
	global_store_dwordx2 v[70:71], v[2:3], off
	v_pk_mul_f32 v[6:7], v[26:27], v[0:1] op_sel_hi:[1,0]
	v_pk_mul_f32 v[8:9], v[28:29], v[0:1] op_sel_hi:[1,0]
	v_pk_mul_f32 v[2:3], v[234:235], v[6:7]
	v_pk_mul_f32 v[4:5], v[236:237], v[8:9]
	v_cvt_pk_bf16_f32 v2, v2, v3
	v_cvt_pk_bf16_f32 v3, v4, v5
	global_store_dwordx2 v[68:69], v[2:3], off
	v_pk_mul_f32 v[6:7], v[22:23], v[0:1] op_sel_hi:[1,0]
	v_pk_mul_f32 v[8:9], v[24:25], v[0:1] op_sel_hi:[1,0]
	v_pk_mul_f32 v[2:3], v[238:239], v[6:7]
	v_pk_mul_f32 v[4:5], v[240:241], v[8:9]
	v_cvt_pk_bf16_f32 v2, v2, v3
	v_cvt_pk_bf16_f32 v3, v4, v5
	global_store_dwordx2 v[66:67], v[2:3], off
	v_pk_mul_f32 v[6:7], v[18:19], v[0:1] op_sel_hi:[1,0]
	v_pk_mul_f32 v[8:9], v[20:21], v[0:1] op_sel_hi:[1,0]
	v_pk_mul_f32 v[2:3], v[242:243], v[6:7]
	v_pk_mul_f32 v[4:5], v[244:245], v[8:9]
	v_cvt_pk_bf16_f32 v2, v2, v3
	v_cvt_pk_bf16_f32 v3, v4, v5
